# rwkv post pass rewritten: one wave per token with 8 channels per lane and row DPP reductions, replacing 64 per-item wave reductions
# speedup vs baseline: 1.0087x; 1.0020x over previous
; __device__ __forceinline__ unsigned f2bf(float f) { return pk2(f, f) & 0xffffu; }
; __device__ __forceinline__ void rwkv_post(const Args& c, int l, int gw, int ngw) {
;     int tid_ = threadIdx.x; asm volatile("" : "+v"(tid_)); unsigned char* wsl = c.ws; asm volatile("" : "+s"(wsl)); int z_ = 0; asm volatile("" : "+s"(z_));
;     float* rwb_ = (l == 0) ? c.out : (float*)(wsl + WS_RW); float* rsc_ = (float*)(wsl + (l == 0 ? WS_SC0 : WS_SC1));
;     const int i = tid_ & 63;
;     const float* Y = (const float*)(wsl + WS_P); const float* V = (const float*)(wsl + WS_V); bf16* MX = (bf16*)(wsl + WS_MIXED);
;     for (int it0 = gw; it0 < M * 8; it0 += 8 * ngw) {
;         float y[8], vv[8], g[8], bs[8], lw[8], lb[8];
; #pragma unroll
;         for (int q = 0; q < 8; ++q) { const int it = it0 + q * ngw; const int itc = (it < M * 8) ? it : it0;
;             const int h = itc & 7; const size_t tok = (size_t)(itc >> 3); const int ch = h * 64 + i;
;             y[q] = Y[tok * (PW / 2) + ch]; vv[q] = V[tok * 512 + ch]; g[q] = bf2f(MX[tok * 2048 + ch]); bs[q] = rsc_[(tok * 8 + h) * 4 + 2];
;             lw[q] = c.in[16 + z_][l * 512 + ch]; lb[q] = c.in[17 + z_][l * 512 + ch]; }
; #pragma unroll
;         for (int q = 0; q < 8; ++q) { const int it = it0 + q * ngw;
;             const float mean = wave_sum_fast(y[q]) * (1.f / 64.f); const float d = y[q] - mean;
;             const float var = wave_sum_fast(d * d) * (1.f / 64.f);
;             const float yn = d * rsqrtf(var + 64e-5f) * lw[q] + lb[q];
;             if (it < M * 8) { const int h = it & 7; const size_t tok = (size_t)(it >> 3); MX[tok * 2048 + h * 64 + i] = (bf16)f2bf((yn + bs[q] * vv[q]) * g[q]); } }
;     }
; }
.LBB0_280:
	s_or_b64 exec, exec, s[2:3]
	v_readfirstlane_b32 s13, v202
	s_ashr_i32 s12, s13, 6
	v_readlane_b32 s0, v252, 32
	v_readlane_b32 s4, v252, 57
	s_add_i32 s0, s12, s0
	v_readlane_b32 s6, v252, 59
	v_readlane_b32 s7, v252, 60
	v_mov_b32_e32 v0, v179
	s_mov_b64 s[8:9], s[6:7]
	s_mov_b32 s6, s15
	s_cmp_gt_i32 s0, 0x1ffff
	s_waitcnt lgkmcnt(0)
	s_barrier
	v_readlane_b32 s1, v251, 61
	v_readlane_b32 s2, v250, 50
	v_readlane_b32 s3, v250, 34
	v_readlane_b32 s4, v251, 0
	v_readlane_b32 s5, v251, 1
	s_nop 3
	s_lshr_b32 s1, s1, 3
	s_load_dwordx4 s[16:19], s[4:5], 0x80
	s_add_u32 s10, s8, 0xa800000
	s_addc_u32 s11, s9, 0
	s_add_u32 s12, s8, 0x29800000
	s_addc_u32 s13, s9, 0
	s_add_u32 s20, s8, 0x18800000
	s_addc_u32 s21, s9, 0
	s_add_u32 s6, s8, s3
	s_addc_u32 s7, s9, 0
	v_and_b32_e32 v2, 63, v179
	v_lshlrev_b32_e32 v3, 5, v2
	v_lshlrev_b32_e32 v4, 4, v2
	v_lshrrev_b32_e32 v5, 3, v2
	v_lshlrev_b32_e32 v5, 4, v5
	v_add_u32_e32 v5, 8, v5
	s_lshl_b32 s2, s2, 2
	v_add_u32_e32 v6, s2, v3
	s_waitcnt lgkmcnt(0)
	global_load_dwordx4 v[8:11], v6, s[16:17]
	global_load_dwordx4 v[12:15], v6, s[16:17] offset:16
	global_load_dwordx4 v[16:19], v6, s[18:19]
	global_load_dwordx4 v[20:23], v6, s[18:19] offset:16
	s_mov_b32 s14, 0x3c800000
.Lpost_loop:
	s_cmp_ge_i32 s0, 0x4000
	s_cbranch_scc1 .Lpost_done
	s_mul_i32 s2, s0, 0x3800
	s_lshl_b32 s3, s0, 11
	s_lshl_b32 s4, s0, 12
	s_lshl_b32 s5, s0, 7
	v_add_u32_e32 v24, s2, v3
	v_add_u32_e32 v25, s3, v3
	v_add_u32_e32 v26, s4, v4
	v_add_u32_e32 v27, s5, v5
	global_load_dwordx4 v[28:31], v24, s[10:11]
	global_load_dwordx4 v[32:35], v24, s[10:11] offset:16
	global_load_dwordx4 v[36:39], v25, s[12:13]
	global_load_dwordx4 v[40:43], v25, s[12:13] offset:16
	global_load_dwordx4 v[44:47], v26, s[20:21]
	global_load_dword v48, v27, s[6:7]
	s_waitcnt vmcnt(0)
	v_add_f32_e32 v49, v28, v29
	v_add_f32_e32 v50, v30, v31
	v_add_f32_e32 v51, v32, v33
	v_add_f32_e32 v52, v34, v35
	v_add_f32_e32 v49, v49, v50
	v_add_f32_e32 v51, v51, v52
	v_add_f32_e32 v49, v49, v51
	s_nop 1
	v_add_f32_dpp v49, v49, v49 quad_perm:[1,0,3,2] row_mask:0xf bank_mask:0xf bound_ctrl:1
	s_nop 1
	v_add_f32_dpp v49, v49, v49 quad_perm:[2,3,0,1] row_mask:0xf bank_mask:0xf bound_ctrl:1
	s_nop 1
	v_add_f32_dpp v49, v49, v49 row_half_mirror row_mask:0xf bank_mask:0xf bound_ctrl:1
	v_mul_f32_e32 v50, s14, v49
	v_sub_f32_e32 v28, v28, v50
	v_sub_f32_e32 v29, v29, v50
	v_sub_f32_e32 v30, v30, v50
	v_sub_f32_e32 v31, v31, v50
	v_sub_f32_e32 v32, v32, v50
	v_sub_f32_e32 v33, v33, v50
	v_sub_f32_e32 v34, v34, v50
	v_sub_f32_e32 v35, v35, v50
	v_mul_f32_e32 v51, v28, v28
	v_fmac_f32_e32 v51, v29, v29
	v_fmac_f32_e32 v51, v30, v30
	v_fmac_f32_e32 v51, v31, v31
	v_fmac_f32_e32 v51, v32, v32
	v_fmac_f32_e32 v51, v33, v33
	v_fmac_f32_e32 v51, v34, v34
	v_fmac_f32_e32 v51, v35, v35
	s_nop 1
	v_add_f32_dpp v51, v51, v51 quad_perm:[1,0,3,2] row_mask:0xf bank_mask:0xf bound_ctrl:1
	s_nop 1
	v_add_f32_dpp v51, v51, v51 quad_perm:[2,3,0,1] row_mask:0xf bank_mask:0xf bound_ctrl:1
	s_nop 1
	v_add_f32_dpp v51, v51, v51 row_half_mirror row_mask:0xf bank_mask:0xf bound_ctrl:1
	v_fmamk_f32 v52, v51, 0x3c800000, v193
	v_rsq_f32_e32 v53, v52
	s_nop 0
	v_mul_f32_e32 v28, v28, v53
	v_fma_f32 v28, v28, v8, v16
	v_fmac_f32_e32 v28, v48, v36
	v_mul_f32_e32 v29, v29, v53
	v_fma_f32 v29, v29, v9, v17
	v_fmac_f32_e32 v29, v48, v37
	v_mul_f32_e32 v30, v30, v53
	v_fma_f32 v30, v30, v10, v18
	v_fmac_f32_e32 v30, v48, v38
	v_mul_f32_e32 v31, v31, v53
	v_fma_f32 v31, v31, v11, v19
	v_fmac_f32_e32 v31, v48, v39
	v_mul_f32_e32 v32, v32, v53
	v_fma_f32 v32, v32, v12, v20
	v_fmac_f32_e32 v32, v48, v40
	v_mul_f32_e32 v33, v33, v53
	v_fma_f32 v33, v33, v13, v21
	v_fmac_f32_e32 v33, v48, v41
	v_mul_f32_e32 v34, v34, v53
	v_fma_f32 v34, v34, v14, v22
	v_fmac_f32_e32 v34, v48, v42
	v_mul_f32_e32 v35, v35, v53
	v_fma_f32 v35, v35, v15, v23
	v_fmac_f32_e32 v35, v48, v43
	v_lshlrev_b32_e32 v54, 16, v44
	v_and_b32_e32 v55, 0xffff0000, v44
	v_mul_f32_e32 v28, v28, v54
	v_mul_f32_e32 v29, v29, v55
	v_cvt_pk_bf16_f32 v56, v28, v29
	v_lshlrev_b32_e32 v54, 16, v45
	v_and_b32_e32 v55, 0xffff0000, v45
	v_mul_f32_e32 v30, v30, v54
	v_mul_f32_e32 v31, v31, v55
	v_cvt_pk_bf16_f32 v57, v30, v31
	v_lshlrev_b32_e32 v54, 16, v46
	v_and_b32_e32 v55, 0xffff0000, v46
	v_mul_f32_e32 v32, v32, v54
	v_mul_f32_e32 v33, v33, v55
	v_cvt_pk_bf16_f32 v58, v32, v33
	v_lshlrev_b32_e32 v54, 16, v47
	v_and_b32_e32 v55, 0xffff0000, v47
	v_mul_f32_e32 v34, v34, v54
	v_mul_f32_e32 v35, v35, v55
	v_cvt_pk_bf16_f32 v59, v34, v35
	global_store_dwordx4 v26, v[56:59], s[20:21]
	s_add_i32 s0, s0, s1
	s_branch .Lpost_loop
.Lpost_done:
.LBB0_297:
	v_readlane_b32 s96, v250, 23
	v_readlane_b32 s58, v253, 52
	v_readlane_b32 s60, v253, 54
	v_readlane_b32 s62, v247, 32
	v_readlane_b32 s66, v253, 57
	v_readlane_b32 s68, v253, 59
	v_readlane_b32 s70, v253, 61
	v_readlane_b32 s72, v253, 63
	v_readlane_b32 s74, v250, 1
	v_readlane_b32 s76, v250, 3
	v_readlane_b32 s78, v250, 5
	v_readlane_b32 s80, v250, 7
	v_readlane_b32 s82, v250, 9
	v_readlane_b32 s84, v250, 11
	v_readlane_b32 s86, v250, 13
	v_readlane_b32 s88, v250, 15
	v_readlane_b32 s90, v250, 17
	v_readlane_b32 s92, v250, 19
	v_readlane_b32 s94, v250, 21
	v_readlane_b32 s97, v250, 24
	s_mov_b64 s[2:3], 0
	v_readlane_b32 s59, v253, 53
	v_readlane_b32 s61, v253, 55
	v_readlane_b32 s63, v247, 33
	v_readlane_b32 s64, v253, 56
	v_readlane_b32 s67, v253, 58
	v_readlane_b32 s69, v253, 60
	v_readlane_b32 s71, v253, 62
	v_readlane_b32 s73, v250, 0
	v_readlane_b32 s75, v250, 2
	v_readlane_b32 s77, v250, 4
	v_readlane_b32 s79, v250, 6
	v_readlane_b32 s81, v250, 8
	v_readlane_b32 s83, v250, 10
	v_readlane_b32 s85, v250, 12
	v_readlane_b32 s87, v250, 14
	v_readlane_b32 s89, v250, 16
	v_readlane_b32 s91, v250, 18
	v_readlane_b32 s93, v250, 20
	v_readlane_b32 s95, v250, 22
	v_readlane_b32 s22, v253, 48
	v_readlane_b32 s65, v250, 25
	v_readlane_b32 s97, v250, 26
	v_readlane_b32 s49, v253, 49
	v_readlane_b32 s50, v253, 50
